# w_down0 weight transposes (176 background tiles) moved from the in_even phase queue to the up0 phase queue, whose idle workgroups have spare time
# speedup vs baseline: 1.0069x; 1.0069x over previous
.LBB0_503:
	s_or_b64 exec, exec, s[0:1]
	v_readlane_b32 s0, v254, 36
	s_waitcnt vmcnt(0) lgkmcnt(0)
	s_barrier
	v_mov_b32_e32 v10, s0
	ds_read_b32 v10, v10
	s_movk_i32 s0, 0x19f
	s_waitcnt lgkmcnt(0)
	s_barrier
	v_cmp_lt_i32_e32 vcc, s0, v10
	v_readfirstlane_b32 s2, v10
	s_mov_b64 s[0:1], -1
	s_cbranch_vccnz .LBB0_498
	v_readlane_b32 s0, v254, 26
	s_cmpk_lt_u32 s2, 0x1a0
	s_nop 0
	v_mov_b32_e32 v10, s0
	ds_read_b64 v[10:11], v10
	s_movk_i32 s0, 0x150
	s_cselect_b32 s0, s0, 0x2b0
	s_cmp_gt_i32 s2, 63
	s_cselect_b32 s18, s0, 0x90
	s_add_i32 s18, s18, s2
	s_cmpk_lt_i32 s18, 0x90
	s_waitcnt lgkmcnt(0)
	v_readfirstlane_b32 s15, v11
	s_cselect_b64 s[6:7], -1, 0
	s_cmpk_gt_i32 s18, 0x8f
	v_readfirstlane_b32 s14, v10
	s_cbranch_scc0 .LBB0_525
	s_cmpk_gt_u32 s18, 0xcf
	s_mov_b64 s[16:17], -1
	s_cbranch_scc0 .LBB0_522
	s_cmpk_gt_u32 s18, 0x14f
	s_cbranch_scc0 .LBB0_519
	s_cmpk_gt_u32 s18, 0x18f
	s_cbranch_scc0 .LBB0_516
	s_cmpk_gt_u32 s18, 0x2ef
	s_cbranch_scc0 .LBB0_513
	s_cmpk_gt_u32 s18, 0x44f
	s_mov_b64 s[0:1], -1
	s_cbranch_scc0 .LBB0_511
	v_readlane_b32 s0, v254, 37
	s_add_i32 s19, s18, 0xfffffbb0
	s_add_u32 s2, s14, 0x2280000
	v_mov_b32_e32 v10, s0
	ds_read_b64 v[10:11], v10
	s_addc_u32 s3, s15, 0
	s_mov_b64 s[0:1], 0
	s_waitcnt lgkmcnt(0)
	v_readfirstlane_b32 s13, v11
	v_readfirstlane_b32 s12, v10

.LBB0_927:
	s_or_b64 exec, exec, s[0:1]
	v_readlane_b32 s0, v254, 36
	s_waitcnt lgkmcnt(0)
	s_barrier
	v_mov_b32_e32 v2, s0
	ds_read_b32 v2, v2
	s_movk_i32 s0, 0x387
	s_waitcnt lgkmcnt(0)
	s_barrier
	v_cmp_lt_i32_e32 vcc, s0, v2
	v_readfirstlane_b32 s10, v2
	s_mov_b64 s[0:1], -1
	s_cbranch_vccnz .LBB0_922
	s_cmpk_gt_i32 s10, 0x2d7
	s_cbranch_scc1 .LBB0_933
	s_cmpk_gt_i32 s10, 0x2cf
	s_cbranch_scc0 .LBB0_933
	v_readlane_b32 s0, v254, 26
	s_nop 1
	v_mov_b32_e32 v2, s0
	ds_read_b64 v[2:3], v2
	s_waitcnt lgkmcnt(0)
	v_readfirstlane_b32 s3, v3
	v_readfirstlane_b32 s2, v2
	s_and_saveexec_b64 s[0:1], s[8:9]
	s_cbranch_execz .LBB0_932
	v_readlane_b32 s15, v254, 52
	s_lshl_b32 s14, s10, 11
	s_add_i32 s11, s14, 0xffe98000
	v_mov_b32_e32 v2, s15
	ds_read_b64 v[2:3], v2
	v_add_u32_e32 v6, s11, v8
	v_ashrrev_i32_e32 v7, 31, v6
	v_lshl_add_u64 v[4:5], v[6:7], 4, s[2:3]
	s_mov_b64 s[2:3], 0x2d80000
	s_add_i32 s11, s14, 0xffe98600
	v_add_u32_e32 v18, s14, v14
	v_lshl_add_u64 v[4:5], v[4:5], 0, s[2:3]
	v_lshlrev_b64 v[6:7], 5, v[6:7]
	s_mov_b64 s[2:3], 0

.LBB0_933:
	s_andn2_b64 vcc, exec, s[0:1]
	s_cbranch_vccnz .LBB0_921
	v_readlane_b32 s0, v254, 26
	s_cmpk_lt_u32 s10, 0x220
	s_nop 0
	v_mov_b32_e32 v2, s0
	ds_read_b64 v[2:3], v2
	s_movk_i32 s0, 0x230
	s_cselect_b32 s0, s0, 0x2e0
	s_cmpk_gt_i32 s10, 0xbf
	s_cselect_b32 s22, s0, 0xd0
	s_add_i32 s22, s22, s10
	s_add_i32 s0, s10, 0x178
	s_cmpk_gt_i32 s10, 0x2d7
	s_cselect_b32 s22, s0, s22
	s_cmpk_lt_i32 s22, 0x90
	s_waitcnt lgkmcnt(0)
	v_readfirstlane_b32 s19, v3
	s_cselect_b64 s[10:11], -1, 0
	s_cmpk_gt_i32 s22, 0x8f
	v_readfirstlane_b32 s18, v2
	s_cbranch_scc0 .LBB0_959
	s_cmpk_gt_u32 s22, 0xcf
	s_mov_b64 s[20:21], -1
	s_cbranch_scc0 .LBB0_956
	s_cmpk_gt_u32 s22, 0x14f
	s_cbranch_scc0 .LBB0_953
	s_cmpk_gt_u32 s22, 0x18f
	s_cbranch_scc0 .LBB0_950
	s_cmpk_gt_u32 s22, 0x2ef
	s_cbranch_scc0 .LBB0_947
	s_cmpk_gt_u32 s22, 0x44f
	s_mov_b64 s[0:1], -1
	s_cbranch_scc0 .LBB0_945
	v_readlane_b32 s0, v254, 37
	s_cmpk_gt_u32 s22, 0x4ff
	s_nop 0
	v_mov_b32_e32 v2, s0
	ds_read_b64 v[2:3], v2
	s_mov_b64 s[0:1], -1
	s_cbranch_scc0 .LBB0_942
	s_add_i32 s23, s22, 0xfffffb00
	s_waitcnt lgkmcnt(0)
	v_readfirstlane_b32 s1, v2
	v_readfirstlane_b32 s0, v3
	s_add_u32 s16, s1, 0xb00000
	s_addc_u32 s17, s0, 0
	s_add_u32 s2, s18, 0x2800000
	s_addc_u32 s3, s19, 0
	s_mov_b64 s[0:1], 0
